# per-loop K-loop code placement: the input-projection and up/gate GEMM loops moved to byte phase 56 (chosen loop by loop with the in-kernel K-loop timer)
# baseline (speedup 1.0000x reference)
; template <class Epi, bool ALIGN_EPI = true, bool SP2 = true>
; __device__ __forceinline__ void gemm_phase(LAS unsigned char* lds, const Gemm g, const Order& S, const Epi& E) {
;     ...
;         const char* nA = has_next ? (const char*)(nxt.z ? g.A1 : g.A0) + (size_t)nxt.pm * tstepA + (size_t)nxt.kt0 * kstep : cA; const char* nB = has_next ? (const char*)(nxt.z ? g.B1 : g.B0) + (size_t)nxt.pn * tstepB + (size_t)nxt.kt0 * kstep : cB;
;         const int nt = cur.nkt;
;         for (int t = 0; t < nt; t += 2) {
;             const bool last = (t == nt - 2);
;             const char* a1 = cA + (size_t)(t + 1) * kstep;
;             const char* a2 = last ? nA : cA + (size_t)(t + 2) * kstep; const char* b2 = last ? nB : cB + (size_t)(t + 2) * kstep;
;             const char* a3 = a2 + kstep; const char* b3 = b2 + kstep;
;     ...
; #pragma unroll
;         for (int a = 0; a < 2; ++a)
; #pragma unroll
;             for (int b = 0; b < 2; ++b)
; #pragma unroll
;                 for (int m = 0; m < 4; ++m)
; #pragma unroll
;                     for (int n = 0; n < 2; ++n) acc[a][b][m][n] = (f32x4){0.f, 0.f, 0.f, 0.f};
;         }
;         cur = nxt; cA = nA; cB = nB; ++ui;
.LBB0_160:
	s_ashr_i32 s89, s88, 31
	s_lshl_b64 s[50:51], s[88:89], 19
	s_add_u32 s52, s23, s50
	s_addc_u32 s53, s24, s51
	s_and_b64 s[50:51], s[92:93], exec
	s_cselect_b32 s91, s53, s13
	s_cselect_b32 s90, s52, s12
	s_ashr_i32 s87, s86, 31
	s_lshl_b64 s[50:51], s[86:87], 19
	s_add_u32 s52, s60, s50
	s_addc_u32 s53, s61, s51
	s_and_b64 s[50:51], s[92:93], exec
	s_cselect_b32 s93, s53, s15
	s_cselect_b32 s92, s52, s14
	s_add_u32 s12, s12, 0x40080
	s_addc_u32 s13, s13, 0
	s_add_u32 s50, s14, 0x100
	v_mov_b32_e32 v2, 0
	s_addc_u32 s51, s15, 0
	s_mov_b32 s52, -2
	v_mov_b32_e32 v3, v2
	v_mov_b32_e32 v4, v2
	v_mov_b32_e32 v5, v2
	v_mov_b32_e32 v6, v2
	v_mov_b32_e32 v7, v2
	v_mov_b32_e32 v8, v2
	v_mov_b32_e32 v9, v2
	v_mov_b32_e32 v14, v2
	v_mov_b32_e32 v15, v2
	v_mov_b32_e32 v16, v2
	v_mov_b32_e32 v17, v2
	v_mov_b32_e32 v22, v2
	v_mov_b32_e32 v23, v2
	v_mov_b32_e32 v24, v2
	v_mov_b32_e32 v25, v2
	v_mov_b32_e32 v30, v2
	v_mov_b32_e32 v31, v2
	v_mov_b32_e32 v32, v2
	v_mov_b32_e32 v33, v2
	v_mov_b32_e32 v38, v2
	v_mov_b32_e32 v39, v2
	v_mov_b32_e32 v40, v2
	v_mov_b32_e32 v41, v2
	v_mov_b32_e32 v46, v2
	v_mov_b32_e32 v47, v2
	v_mov_b32_e32 v48, v2
	v_mov_b32_e32 v49, v2
	v_mov_b32_e32 v54, v2
	v_mov_b32_e32 v55, v2
	v_mov_b32_e32 v56, v2
	v_mov_b32_e32 v57, v2
	v_mov_b32_e32 v10, v2
	v_mov_b32_e32 v11, v2
	v_mov_b32_e32 v12, v2
	v_mov_b32_e32 v13, v2
	v_mov_b32_e32 v18, v2
	v_mov_b32_e32 v19, v2
	v_mov_b32_e32 v20, v2
	v_mov_b32_e32 v21, v2
	v_mov_b32_e32 v26, v2
	v_mov_b32_e32 v27, v2
	v_mov_b32_e32 v28, v2
	v_mov_b32_e32 v29, v2
	v_mov_b32_e32 v34, v2
	v_mov_b32_e32 v35, v2
	v_mov_b32_e32 v36, v2
	v_mov_b32_e32 v37, v2
	v_mov_b32_e32 v42, v2
	v_mov_b32_e32 v43, v2
	v_mov_b32_e32 v44, v2
	v_mov_b32_e32 v45, v2
	v_mov_b32_e32 v50, v2
	v_mov_b32_e32 v51, v2
	v_mov_b32_e32 v52, v2
	v_mov_b32_e32 v53, v2
	v_mov_b32_e32 v58, v2
	v_mov_b32_e32 v59, v2
	v_mov_b32_e32 v60, v2
	v_mov_b32_e32 v61, v2
	v_mov_b32_e32 v62, v2
	v_mov_b32_e32 v63, v2
	v_mov_b32_e32 v64, v2
	v_mov_b32_e32 v65, v2
	v_mov_b32_e32 v66, v2
	v_mov_b32_e32 v67, v2
	v_mov_b32_e32 v68, v2
	v_mov_b32_e32 v69, v2
	v_mov_b32_e32 v70, v2
	v_mov_b32_e32 v71, v2
	v_mov_b32_e32 v72, v2
	v_mov_b32_e32 v73, v2
	v_mov_b32_e32 v82, v2
	v_mov_b32_e32 v83, v2
	v_mov_b32_e32 v84, v2
	v_mov_b32_e32 v85, v2
	v_mov_b32_e32 v86, v2
	v_mov_b32_e32 v87, v2
	v_mov_b32_e32 v88, v2
	v_mov_b32_e32 v89, v2
	v_mov_b32_e32 v98, v2
	v_mov_b32_e32 v99, v2
	v_mov_b32_e32 v100, v2
	v_mov_b32_e32 v101, v2
	v_mov_b32_e32 v102, v2
	v_mov_b32_e32 v103, v2
	v_mov_b32_e32 v104, v2
	v_mov_b32_e32 v105, v2
	v_mov_b32_e32 v114, v2
	v_mov_b32_e32 v115, v2
	v_mov_b32_e32 v116, v2
	v_mov_b32_e32 v117, v2
	v_mov_b32_e32 v118, v2
	v_mov_b32_e32 v119, v2
	v_mov_b32_e32 v120, v2
	v_mov_b32_e32 v121, v2
	v_mov_b32_e32 v74, v2
	v_mov_b32_e32 v75, v2
	v_mov_b32_e32 v76, v2
	v_mov_b32_e32 v77, v2
	v_mov_b32_e32 v78, v2
	v_mov_b32_e32 v79, v2
	v_mov_b32_e32 v80, v2
	v_mov_b32_e32 v81, v2
	v_mov_b32_e32 v90, v2
	v_mov_b32_e32 v91, v2
	v_mov_b32_e32 v92, v2
	v_mov_b32_e32 v93, v2
	v_mov_b32_e32 v94, v2
	v_mov_b32_e32 v95, v2
	v_mov_b32_e32 v96, v2
	v_mov_b32_e32 v97, v2
	v_mov_b32_e32 v106, v2
	v_mov_b32_e32 v107, v2
	v_mov_b32_e32 v108, v2
	v_mov_b32_e32 v109, v2
	v_mov_b32_e32 v110, v2
	v_mov_b32_e32 v111, v2
	v_mov_b32_e32 v112, v2
	v_mov_b32_e32 v113, v2
	v_mov_b32_e32 v122, v2
	v_mov_b32_e32 v123, v2
	v_mov_b32_e32 v124, v2
	v_mov_b32_e32 v125, v2
	v_mov_b32_e32 v126, v2
	v_mov_b32_e32 v127, v2
	v_mov_b32_e32 v128, v2
	v_mov_b32_e32 v129, v2
	.p2align	6
	s_nop 0
	s_nop 0
	s_nop 0
	s_nop 0
	s_nop 0
	s_nop 0
	s_nop 0
	s_nop 0
	s_nop 0
	s_nop 0
	s_nop 0
	s_nop 0
	s_nop 0
	s_nop 0

; template <class Epi, bool ALIGN_EPI = true, bool SP2 = true>
; __device__ __forceinline__ void gemm_phase(LAS unsigned char* lds, const Gemm g, const Order& S, const Epi& E) {
;     ...
;         const char* nA = has_next ? (const char*)(nxt.z ? g.A1 : g.A0) + (size_t)nxt.pm * tstepA + (size_t)nxt.kt0 * kstep : cA; const char* nB = has_next ? (const char*)(nxt.z ? g.B1 : g.B0) + (size_t)nxt.pn * tstepB + (size_t)nxt.kt0 * kstep : cB;
;         const int nt = cur.nkt;
;         for (int t = 0; t < nt; t += 2) {
;             const bool last = (t == nt - 2);
;             const char* a1 = cA + (size_t)(t + 1) * kstep;
;             const char* a2 = last ? nA : cA + (size_t)(t + 2) * kstep; const char* b2 = last ? nB : cB + (size_t)(t + 2) * kstep;
;             const char* a3 = a2 + kstep; const char* b3 = b2 + kstep;
;     ...
; #pragma unroll
;         for (int a = 0; a < 2; ++a)
; #pragma unroll
;             for (int b = 0; b < 2; ++b)
; #pragma unroll
;                 for (int m = 0; m < 4; ++m)
; #pragma unroll
;                     for (int n = 0; n < 2; ++n) acc[a][b][m][n] = (f32x4){0.f, 0.f, 0.f, 0.f};
;         }
;         cur = nxt; cA = nA; cB = nB; ++ui;
.LBB0_879:
	s_ashr_i32 s85, s84, 31
	s_lshl_b64 s[54:55], s[84:85], 19
	s_add_u32 s11, s50, s54
	s_addc_u32 s35, s51, s55
	s_and_b64 s[54:55], s[88:89], exec
	s_cselect_b32 s87, s35, s13
	s_cselect_b32 s86, s11, s12
	s_ashr_i32 s83, s82, 31
	s_lshl_b64 s[54:55], s[82:83], 19
	s_add_u32 s11, s52, s54
	s_addc_u32 s35, s53, s55
	s_and_b64 s[54:55], s[88:89], exec
	s_cselect_b32 s89, s35, s93
	s_cselect_b32 s88, s11, s92
	s_add_u32 s12, s12, 0x40080
	s_addc_u32 s13, s13, 0
	s_add_u32 s11, s92, 0x100
	v_mov_b32_e32 v2, 0
	s_addc_u32 s35, s93, 0
	s_mov_b32 s54, -2
	v_mov_b32_e32 v3, v2
	v_mov_b32_e32 v4, v2
	v_mov_b32_e32 v5, v2
	v_mov_b32_e32 v14, v2
	v_mov_b32_e32 v15, v2
	v_mov_b32_e32 v16, v2
	v_mov_b32_e32 v17, v2
	v_mov_b32_e32 v18, v2
	v_mov_b32_e32 v19, v2
	v_mov_b32_e32 v20, v2
	v_mov_b32_e32 v21, v2
	v_mov_b32_e32 v30, v2
	v_mov_b32_e32 v31, v2
	v_mov_b32_e32 v32, v2
	v_mov_b32_e32 v33, v2
	v_mov_b32_e32 v34, v2
	v_mov_b32_e32 v35, v2
	v_mov_b32_e32 v36, v2
	v_mov_b32_e32 v37, v2
	v_mov_b32_e32 v46, v2
	v_mov_b32_e32 v47, v2
	v_mov_b32_e32 v48, v2
	v_mov_b32_e32 v49, v2
	v_mov_b32_e32 v82, v2
	v_mov_b32_e32 v83, v2
	v_mov_b32_e32 v84, v2
	v_mov_b32_e32 v85, v2
	v_mov_b32_e32 v94, v2
	v_mov_b32_e32 v95, v2
	v_mov_b32_e32 v96, v2
	v_mov_b32_e32 v97, v2
	v_mov_b32_e32 v6, v2
	v_mov_b32_e32 v7, v2
	v_mov_b32_e32 v8, v2
	v_mov_b32_e32 v9, v2
	v_mov_b32_e32 v10, v2
	v_mov_b32_e32 v11, v2
	v_mov_b32_e32 v12, v2
	v_mov_b32_e32 v13, v2
	v_mov_b32_e32 v22, v2
	v_mov_b32_e32 v23, v2
	v_mov_b32_e32 v24, v2
	v_mov_b32_e32 v25, v2
	v_mov_b32_e32 v26, v2
	v_mov_b32_e32 v27, v2
	v_mov_b32_e32 v28, v2
	v_mov_b32_e32 v29, v2
	v_mov_b32_e32 v38, v2
	v_mov_b32_e32 v39, v2
	v_mov_b32_e32 v40, v2
	v_mov_b32_e32 v41, v2
	v_mov_b32_e32 v42, v2
	v_mov_b32_e32 v43, v2
	v_mov_b32_e32 v44, v2
	v_mov_b32_e32 v45, v2
	v_mov_b32_e32 v86, v2
	v_mov_b32_e32 v87, v2
	v_mov_b32_e32 v88, v2
	v_mov_b32_e32 v89, v2
	v_mov_b32_e32 v90, v2
	v_mov_b32_e32 v91, v2
	v_mov_b32_e32 v92, v2
	v_mov_b32_e32 v93, v2
	v_mov_b32_e32 v106, v2
	v_mov_b32_e32 v107, v2
	v_mov_b32_e32 v108, v2
	v_mov_b32_e32 v109, v2
	v_mov_b32_e32 v114, v2
	v_mov_b32_e32 v115, v2
	v_mov_b32_e32 v116, v2
	v_mov_b32_e32 v117, v2
	v_mov_b32_e32 v122, v2
	v_mov_b32_e32 v123, v2
	v_mov_b32_e32 v124, v2
	v_mov_b32_e32 v125, v2
	v_mov_b32_e32 v130, v2
	v_mov_b32_e32 v131, v2
	v_mov_b32_e32 v132, v2
	v_mov_b32_e32 v133, v2
	v_mov_b32_e32 v138, v2
	v_mov_b32_e32 v139, v2
	v_mov_b32_e32 v140, v2
	v_mov_b32_e32 v141, v2
	v_mov_b32_e32 v146, v2
	v_mov_b32_e32 v147, v2
	v_mov_b32_e32 v148, v2
	v_mov_b32_e32 v149, v2
	v_mov_b32_e32 v154, v2
	v_mov_b32_e32 v155, v2
	v_mov_b32_e32 v156, v2
	v_mov_b32_e32 v157, v2
	v_mov_b32_e32 v158, v2
	v_mov_b32_e32 v159, v2
	v_mov_b32_e32 v160, v2
	v_mov_b32_e32 v161, v2
	v_mov_b32_e32 v98, v2
	v_mov_b32_e32 v99, v2
	v_mov_b32_e32 v100, v2
	v_mov_b32_e32 v101, v2
	v_mov_b32_e32 v102, v2
	v_mov_b32_e32 v103, v2
	v_mov_b32_e32 v104, v2
	v_mov_b32_e32 v105, v2
	v_mov_b32_e32 v110, v2
	v_mov_b32_e32 v111, v2
	v_mov_b32_e32 v112, v2
	v_mov_b32_e32 v113, v2
	v_mov_b32_e32 v118, v2
	v_mov_b32_e32 v119, v2
	v_mov_b32_e32 v120, v2
	v_mov_b32_e32 v121, v2
	v_mov_b32_e32 v126, v2
	v_mov_b32_e32 v127, v2
	v_mov_b32_e32 v128, v2
	v_mov_b32_e32 v129, v2
	v_mov_b32_e32 v134, v2
	v_mov_b32_e32 v135, v2
	v_mov_b32_e32 v136, v2
	v_mov_b32_e32 v137, v2
	v_mov_b32_e32 v142, v2
	v_mov_b32_e32 v143, v2
	v_mov_b32_e32 v144, v2
	v_mov_b32_e32 v145, v2
	v_mov_b32_e32 v150, v2
	v_mov_b32_e32 v151, v2
	v_mov_b32_e32 v152, v2
	v_mov_b32_e32 v153, v2
	.p2align	6
	s_nop 0
	s_nop 0
	s_nop 0
	s_nop 0
	s_nop 0
	s_nop 0
	s_nop 0
	s_nop 0
	s_nop 0
	s_nop 0
	s_nop 0
	s_nop 0
	s_nop 0
	s_nop 0
